# conversion loops no longer wait for the previous tile's store acks (vmcnt(4) instead of vmcnt(0) on the steady-state path); on top of sink-fix/noflush stack
# baseline (speedup 1.0000x reference)
.LBB0_303:
	v_ashrrev_i32_e32 v107, 31, v121
	v_mul_lo_u32 v122, s7, v121
	v_mul_lo_u32 v107, s6, v107
	v_mad_u64_u32 v[120:121], s[6:7], s6, v121, 0
	v_add3_u32 v121, v121, v107, v122
	v_lshl_add_u64 v[108:109], v[120:121], 1, v[108:109]
	global_store_dwordx4 v[108:109], v[102:105], off
	s_waitcnt lgkmcnt(0)
	s_cmp_eq_u32 s99, 2
	s_cbranch_scc1 .LBB0_360
	s_waitcnt vmcnt(4)
	s_branch .Lcv_mid2_G5

.Lcv_mid2_G5:
	ds_write2_b32 v19, v2, v3 offset1:1
	ds_write2_b32 v19, v4, v5 offset0:2 offset1:3
	v_add_u32_e32 v2, 0x420, v19
	ds_write2_b32 v2, v20, v21 offset1:1
	v_add_u32_e32 v2, 0x428, v19
	ds_write2_b32 v2, v22, v23 offset1:1
	v_add_u32_e32 v2, 0x840, v19
	ds_write2_b32 v2, v24, v25 offset1:1
	v_add_u32_e32 v2, 0x848, v19
	ds_write2_b32 v2, v26, v27 offset1:1
	v_add_u32_e32 v2, 0xc60, v19
	ds_write2_b32 v2, v28, v29 offset1:1
	v_add_u32_e32 v2, 0xc68, v19
	ds_write2_b32 v2, v30, v31 offset1:1
	v_add_u32_e32 v2, 0x1080, v19
	ds_write2_b32 v2, v32, v33 offset1:1
	v_add_u32_e32 v2, 0x1088, v19
	ds_write2_b32 v2, v34, v35 offset1:1
	v_add_u32_e32 v2, 0x14a0, v19
	ds_write2_b32 v2, v36, v37 offset1:1
	v_add_u32_e32 v2, 0x14a8, v19
	ds_write2_b32 v2, v38, v39 offset1:1
	v_add_u32_e32 v2, 0x18c0, v19
	ds_write2_b32 v2, v40, v41 offset1:1
	v_add_u32_e32 v2, 0x18c8, v19
	ds_write2_b32 v2, v42, v43 offset1:1
	v_add_u32_e32 v2, 0x1ce0, v19
	ds_write2_b32 v2, v44, v45 offset1:1
	v_add_u32_e32 v2, 0x1ce8, v19
	ds_write2_b32 v2, v46, v47 offset1:1
	s_waitcnt lgkmcnt(0)
	s_nop 1
	v_readlane_b32 s100, v255, 40
	v_readlane_b32 s101, v255, 41
	s_nop 1
	v_writelane_b32 v255, s100, 16
	v_writelane_b32 v255, s101, 17
	s_nop 1
	v_readlane_b32 s100, v255, 42
	v_readlane_b32 s101, v255, 43
	s_nop 1
	v_writelane_b32 v255, s100, 18
	v_writelane_b32 v255, s101, 19
	s_nop 1
	v_readlane_b32 s100, v255, 44
	v_readlane_b32 s101, v255, 45
	s_nop 1
	v_writelane_b32 v255, s100, 20
	v_writelane_b32 v255, s101, 21
	s_nop 1
	v_readlane_b32 s100, v255, 46
	v_readlane_b32 s101, v255, 47
	s_nop 1
	v_writelane_b32 v255, s100, 22
	v_writelane_b32 v255, s101, 23
	s_nop 1
	v_readlane_b32 s100, v255, 48
	v_readlane_b32 s101, v255, 49
	s_nop 1
	v_writelane_b32 v255, s100, 24
	v_writelane_b32 v255, s101, 25
	s_nop 1
	v_readlane_b32 s100, v255, 50
	v_readlane_b32 s101, v255, 51
	s_nop 1
	v_writelane_b32 v255, s100, 26
	v_writelane_b32 v255, s101, 27
	s_nop 1
	v_readlane_b32 s100, v255, 52
	s_nop 1
	v_writelane_b32 v255, s100, 28
	s_nop 1
	s_add_i32 s19, s19, s20
	s_cmp_lt_i32 s19, s18
	s_cbranch_scc0 .Lcv_drain_G5
	s_mov_b32 s99, 1
	s_branch .LBB0_304

.LBB0_671:
	v_ashrrev_i32_e32 v107, 31, v121
	v_mul_lo_u32 v122, s5, v121
	v_mul_lo_u32 v107, s4, v107
	v_mad_u64_u32 v[120:121], s[4:5], s4, v121, 0
	v_add3_u32 v121, v121, v107, v122
	v_lshl_add_u64 v[108:109], v[120:121], 1, v[108:109]
	global_store_dwordx4 v[108:109], v[102:105], off
	s_waitcnt lgkmcnt(0)
	s_cmp_eq_u32 s99, 2
	s_cbranch_scc1 .LBB0_728
	s_waitcnt vmcnt(4)
	s_branch .Lcv_mid2_G1

.Lcv_mid2_G1:
	ds_write2_b32 v19, v2, v3 offset1:1
	ds_write2_b32 v19, v4, v5 offset0:2 offset1:3
	v_add_u32_e32 v2, 0x420, v19
	ds_write2_b32 v2, v20, v21 offset1:1
	v_add_u32_e32 v2, 0x428, v19
	ds_write2_b32 v2, v22, v23 offset1:1
	v_add_u32_e32 v2, 0x840, v19
	ds_write2_b32 v2, v24, v25 offset1:1
	v_add_u32_e32 v2, 0x848, v19
	ds_write2_b32 v2, v26, v27 offset1:1
	v_add_u32_e32 v2, 0xc60, v19
	ds_write2_b32 v2, v28, v29 offset1:1
	v_add_u32_e32 v2, 0xc68, v19
	ds_write2_b32 v2, v30, v31 offset1:1
	v_add_u32_e32 v2, 0x1080, v19
	ds_write2_b32 v2, v32, v33 offset1:1
	v_add_u32_e32 v2, 0x1088, v19
	ds_write2_b32 v2, v34, v35 offset1:1
	v_add_u32_e32 v2, 0x14a0, v19
	ds_write2_b32 v2, v36, v37 offset1:1
	v_add_u32_e32 v2, 0x14a8, v19
	ds_write2_b32 v2, v38, v39 offset1:1
	v_add_u32_e32 v2, 0x18c0, v19
	ds_write2_b32 v2, v40, v41 offset1:1
	v_add_u32_e32 v2, 0x18c8, v19
	ds_write2_b32 v2, v42, v43 offset1:1
	v_add_u32_e32 v2, 0x1ce0, v19
	ds_write2_b32 v2, v44, v45 offset1:1
	v_add_u32_e32 v2, 0x1ce8, v19
	ds_write2_b32 v2, v46, v47 offset1:1
	s_waitcnt lgkmcnt(0)
	s_nop 1
	v_readlane_b32 s100, v255, 40
	v_readlane_b32 s101, v255, 41
	s_nop 1
	v_writelane_b32 v255, s100, 16
	v_writelane_b32 v255, s101, 17
	s_nop 1
	v_readlane_b32 s100, v255, 42
	v_readlane_b32 s101, v255, 43
	s_nop 1
	v_writelane_b32 v255, s100, 18
	v_writelane_b32 v255, s101, 19
	s_nop 1
	v_readlane_b32 s100, v255, 44
	v_readlane_b32 s101, v255, 45
	s_nop 1
	v_writelane_b32 v255, s100, 20
	v_writelane_b32 v255, s101, 21
	s_nop 1
	v_readlane_b32 s100, v255, 46
	v_readlane_b32 s101, v255, 47
	s_nop 1
	v_writelane_b32 v255, s100, 22
	v_writelane_b32 v255, s101, 23
	s_nop 1
	v_readlane_b32 s100, v255, 48
	v_readlane_b32 s101, v255, 49
	s_nop 1
	v_writelane_b32 v255, s100, 24
	v_writelane_b32 v255, s101, 25
	s_nop 1
	v_readlane_b32 s100, v255, 50
	v_readlane_b32 s101, v255, 51
	s_nop 1
	v_writelane_b32 v255, s100, 26
	v_writelane_b32 v255, s101, 27
	s_nop 1
	v_readlane_b32 s100, v255, 52
	s_nop 1
	v_writelane_b32 v255, s100, 28
	s_nop 1
	s_add_i32 s17, s17, s18
	s_cmp_lt_i32 s17, s16
	s_cbranch_scc0 .Lcv_drain_G1
	s_mov_b32 s99, 1
	s_branch .LBB0_672
